# sample attention tile body: packed f32 multiplies (v_pk_mul_f32) replaced by scalar v_mul_f32 beside the MFMAs
# baseline (speedup 1.0000x reference)
.Lsa_nd8:
	s_nop 5
	v_mul_f32_e32 v206, v227, v227
	v_mul_f32_e32 v209, v231, v231
	v_fmac_f32_e32 v206, v226, v226
	v_fmac_f32_e32 v209, v230, v230
	v_fmac_f32_e32 v206, v228, v228
	v_fmac_f32_e32 v209, v232, v232
	v_fmac_f32_e32 v206, v229, v229
	v_fmac_f32_e32 v209, v233, v233
	v_add_f32_e32 v206, v206, v209
	v_mul_f32_e32 v209, v235, v235
	v_fmac_f32_e32 v209, v234, v234
	v_fmac_f32_e32 v209, v236, v236
	v_fmac_f32_e32 v209, v237, v237
	v_add_f32_e32 v206, v206, v209
	v_mul_f32_e32 v209, v239, v239
	v_fmac_f32_e32 v209, v238, v238
	v_fmac_f32_e32 v209, v240, v240
	v_fmac_f32_e32 v209, v241, v241
	v_add_f32_e32 v206, v206, v209
	v_mov_b32_e32 v209, v206
	s_nop 1
	v_permlane16_swap_b32_e32 v206, v209
	v_add_f32_e32 v206, v206, v209
	v_mov_b32_e32 v209, v206
	s_nop 1
	v_permlane32_swap_b32_e32 v206, v209
	v_add_f32_e32 v206, v206, v209
	v_mov_b32_e32 v209, 0x358637bd
	v_fmamk_f32 v206, v206, 0x3c800000, v209
	v_rsq_f32_e32 v206, v206
	s_nop 0
	v_mul_f32_e32 v226, v226, v206
	v_mul_f32_e32 v227, v227, v206
	v_mul_f32_e32 v228, v228, v206
	v_mul_f32_e32 v229, v229, v206
	v_mul_f32_e32 v230, v230, v206
	v_mul_f32_e32 v231, v231, v206
	v_mul_f32_e32 v232, v232, v206
	v_mul_f32_e32 v233, v233, v206
	v_mul_f32_e32 v234, v234, v206
	v_mul_f32_e32 v235, v235, v206
	v_mul_f32_e32 v236, v236, v206
	v_mul_f32_e32 v237, v237, v206
	v_mul_f32_e32 v238, v238, v206
	v_mul_f32_e32 v239, v239, v206
	v_mul_f32_e32 v240, v240, v206
	v_mul_f32_e32 v241, v241, v206
	v_cvt_pk_bf16_f32 v226, v226, v227
	v_cvt_pk_bf16_f32 v227, v228, v229
	v_cvt_pk_bf16_f32 v228, v230, v231
	v_cvt_pk_bf16_f32 v229, v232, v233
	v_cvt_pk_bf16_f32 v234, v234, v235
	v_cvt_pk_bf16_f32 v235, v236, v237
	v_cvt_pk_bf16_f32 v236, v238, v239
	v_cvt_pk_bf16_f32 v237, v240, v241
	ds_read_b128 v[230:233], v49 offset:4096
	ds_read_b128 v[238:241], v48 offset:4096
	s_waitcnt lgkmcnt(2)
	v_mfma_f32_16x16x32_bf16 v[38:41], v[226:229], v[34:37], 0
	v_mfma_f32_16x16x32_bf16 v[38:41], v[234:237], v[182:185], v[38:41]
	v_mfma_f32_16x16x32_bf16 v[38:41], v[186:189], v[202:205], v[38:41]
	ds_read_b128 v[34:37], v47 offset:4096
	ds_read_b128 v[182:185], v46 offset:4096
	s_waitcnt lgkmcnt(2)
	v_mfma_f32_16x16x32_bf16 v[226:229], v[50:53], v[230:233], 0
	v_mfma_f32_16x16x32_bf16 v[234:237], v[82:85], v[230:233], 0
	v_mfma_f32_16x16x32_bf16 v[186:189], v[114:117], v[230:233], 0
	v_mfma_f32_16x16x32_bf16 v[202:205], v[146:149], v[230:233], 0
	v_mfma_f32_16x16x32_bf16 v[226:229], v[54:57], v[238:241], v[226:229]
	v_mfma_f32_16x16x32_bf16 v[234:237], v[86:89], v[238:241], v[234:237]
	v_mfma_f32_16x16x32_bf16 v[186:189], v[118:121], v[238:241], v[186:189]
	v_mfma_f32_16x16x32_bf16 v[202:205], v[150:153], v[238:241], v[202:205]
	ds_read_b128 v[230:233], v49 offset:20480
	ds_read_b128 v[238:241], v48 offset:20480
	s_waitcnt lgkmcnt(2)
	v_mfma_f32_16x16x32_bf16 v[226:229], v[58:61], v[34:37], v[226:229]
	v_mfma_f32_16x16x32_bf16 v[234:237], v[90:93], v[34:37], v[234:237]
	v_mfma_f32_16x16x32_bf16 v[186:189], v[122:125], v[34:37], v[186:189]
	v_mfma_f32_16x16x32_bf16 v[202:205], v[154:157], v[34:37], v[202:205]
	v_mfma_f32_16x16x32_bf16 v[226:229], v[62:65], v[182:185], v[226:229]
	v_mfma_f32_16x16x32_bf16 v[234:237], v[94:97], v[182:185], v[234:237]
	v_mfma_f32_16x16x32_bf16 v[186:189], v[126:129], v[182:185], v[186:189]
	v_mfma_f32_16x16x32_bf16 v[202:205], v[158:161], v[182:185], v[202:205]
	ds_read_b128 v[34:37], v47 offset:20480
	ds_read_b128 v[182:185], v46 offset:20480
	s_waitcnt lgkmcnt(2)
	v_mfma_f32_16x16x32_bf16 v[226:229], v[66:69], v[230:233], v[226:229]
	v_mfma_f32_16x16x32_bf16 v[234:237], v[98:101], v[230:233], v[234:237]
	v_mfma_f32_16x16x32_bf16 v[186:189], v[130:133], v[230:233], v[186:189]
	v_mfma_f32_16x16x32_bf16 v[202:205], v[162:165], v[230:233], v[202:205]
	v_mfma_f32_16x16x32_bf16 v[226:229], v[70:73], v[238:241], v[226:229]
	v_mfma_f32_16x16x32_bf16 v[234:237], v[102:105], v[238:241], v[234:237]
	v_mfma_f32_16x16x32_bf16 v[186:189], v[134:137], v[238:241], v[186:189]
	v_mfma_f32_16x16x32_bf16 v[202:205], v[166:169], v[238:241], v[202:205]
	ds_read2_b64 v[230:233], v207 offset1:4
	ds_read2_b64 v[238:241], v207 offset0:8 offset1:12
	s_waitcnt lgkmcnt(2)
	v_mfma_f32_16x16x32_bf16 v[226:229], v[74:77], v[34:37], v[226:229]
	v_mfma_f32_16x16x32_bf16 v[234:237], v[106:109], v[34:37], v[234:237]
	v_mfma_f32_16x16x32_bf16 v[186:189], v[138:141], v[34:37], v[186:189]
	v_mfma_f32_16x16x32_bf16 v[202:205], v[170:173], v[34:37], v[202:205]
	v_mfma_f32_16x16x32_bf16 v[226:229], v[78:81], v[182:185], v[226:229]
	v_mfma_f32_16x16x32_bf16 v[234:237], v[110:113], v[182:185], v[234:237]
	v_mfma_f32_16x16x32_bf16 v[186:189], v[142:145], v[182:185], v[186:189]
	v_mfma_f32_16x16x32_bf16 v[202:205], v[174:177], v[182:185], v[202:205]
	ds_read_b128 v[34:37], v225 offset:1280
	ds_read_b128 v[182:185], v208 offset:47232
	s_nop 5
	v_mul_f32_e32 v206, v227, v227
	v_mul_f32_e32 v209, v235, v235
	v_fmac_f32_e32 v206, v226, v226
	v_fmac_f32_e32 v209, v234, v234
	v_fmac_f32_e32 v206, v228, v228
	v_fmac_f32_e32 v209, v236, v236
	v_fmac_f32_e32 v206, v229, v229
	v_fmac_f32_e32 v209, v237, v237
	v_add_f32_e32 v206, v206, v209
	v_mul_f32_e32 v209, v187, v187
	v_fmac_f32_e32 v209, v186, v186
	v_fmac_f32_e32 v209, v188, v188
	v_fmac_f32_e32 v209, v189, v189
	v_add_f32_e32 v206, v206, v209
	v_mul_f32_e32 v209, v203, v203
	v_fmac_f32_e32 v209, v202, v202
	v_fmac_f32_e32 v209, v204, v204
	v_fmac_f32_e32 v209, v205, v205
	v_add_f32_e32 v206, v206, v209
	v_mov_b32_e32 v209, v206
	s_nop 1
	v_permlane16_swap_b32_e32 v206, v209
	v_add_f32_e32 v206, v206, v209
	v_mov_b32_e32 v209, v206
	s_nop 1
	v_permlane32_swap_b32_e32 v206, v209
	v_add_f32_e32 v206, v206, v209
	v_mov_b32_e32 v209, 0x358637bd
	v_fmamk_f32 v206, v206, 0x3c800000, v209
	v_rsq_f32_e32 v206, v206
	s_nop 0
	v_mul_f32_e32 v226, v226, v206
	v_mul_f32_e32 v227, v227, v206
	v_mul_f32_e32 v228, v228, v206
	v_mul_f32_e32 v229, v229, v206
	v_mul_f32_e32 v234, v234, v206
	v_mul_f32_e32 v235, v235, v206
	v_mul_f32_e32 v236, v236, v206
	v_mul_f32_e32 v237, v237, v206
	v_mul_f32_e32 v186, v186, v206
	v_mul_f32_e32 v187, v187, v206
	v_mul_f32_e32 v188, v188, v206
	v_mul_f32_e32 v189, v189, v206
	v_mul_f32_e32 v202, v202, v206
	v_mul_f32_e32 v203, v203, v206
	v_mul_f32_e32 v204, v204, v206
	v_mul_f32_e32 v205, v205, v206
	v_cvt_pk_bf16_f32 v226, v226, v227
	v_cvt_pk_bf16_f32 v227, v228, v229
	v_cvt_pk_bf16_f32 v228, v234, v235
	v_cvt_pk_bf16_f32 v229, v236, v237
	v_cvt_pk_bf16_f32 v186, v186, v187
	v_cvt_pk_bf16_f32 v187, v188, v189
	v_cvt_pk_bf16_f32 v188, v202, v203
	v_cvt_pk_bf16_f32 v189, v204, v205
	ds_read_b128 v[234:237], v49 offset:8192
	ds_read_b128 v[202:205], v48 offset:8192
	s_waitcnt lgkmcnt(2)
	v_mfma_f32_16x16x32_bf16 v[178:181], v[226:229], v[230:233], 0
	v_mfma_f32_16x16x32_bf16 v[178:181], v[186:189], v[238:241], v[178:181]
	v_mfma_f32_16x16x32_bf16 v[178:181], v[34:37], v[182:185], v[178:181]
	ds_read_b128 v[230:233], v47 offset:8192
	ds_read_b128 v[238:241], v46 offset:8192
	s_waitcnt lgkmcnt(2)
	v_mfma_f32_16x16x32_bf16 v[226:229], v[50:53], v[234:237], 0
	v_mfma_f32_16x16x32_bf16 v[186:189], v[82:85], v[234:237], 0
	v_mfma_f32_16x16x32_bf16 v[34:37], v[114:117], v[234:237], 0
	v_mfma_f32_16x16x32_bf16 v[182:185], v[146:149], v[234:237], 0
	v_mfma_f32_16x16x32_bf16 v[226:229], v[54:57], v[202:205], v[226:229]
	v_mfma_f32_16x16x32_bf16 v[186:189], v[86:89], v[202:205], v[186:189]
	v_mfma_f32_16x16x32_bf16 v[34:37], v[118:121], v[202:205], v[34:37]
	v_mfma_f32_16x16x32_bf16 v[182:185], v[150:153], v[202:205], v[182:185]
	ds_read_b128 v[234:237], v49 offset:24576
	ds_read_b128 v[202:205], v48 offset:24576
	s_waitcnt lgkmcnt(2)
	v_mfma_f32_16x16x32_bf16 v[226:229], v[58:61], v[230:233], v[226:229]
	v_mfma_f32_16x16x32_bf16 v[186:189], v[90:93], v[230:233], v[186:189]
	v_mfma_f32_16x16x32_bf16 v[34:37], v[122:125], v[230:233], v[34:37]
	v_mfma_f32_16x16x32_bf16 v[182:185], v[154:157], v[230:233], v[182:185]
	v_mfma_f32_16x16x32_bf16 v[226:229], v[62:65], v[238:241], v[226:229]
	v_mfma_f32_16x16x32_bf16 v[186:189], v[94:97], v[238:241], v[186:189]
	v_mfma_f32_16x16x32_bf16 v[34:37], v[126:129], v[238:241], v[34:37]
	v_mfma_f32_16x16x32_bf16 v[182:185], v[158:161], v[238:241], v[182:185]
	ds_read_b128 v[230:233], v47 offset:24576
	ds_read_b128 v[238:241], v46 offset:24576
	s_waitcnt lgkmcnt(2)
	v_mfma_f32_16x16x32_bf16 v[226:229], v[66:69], v[234:237], v[226:229]
	v_mfma_f32_16x16x32_bf16 v[186:189], v[98:101], v[234:237], v[186:189]
	v_mfma_f32_16x16x32_bf16 v[34:37], v[130:133], v[234:237], v[34:37]
	v_mfma_f32_16x16x32_bf16 v[182:185], v[162:165], v[234:237], v[182:185]
	v_mfma_f32_16x16x32_bf16 v[226:229], v[70:73], v[202:205], v[226:229]
	v_mfma_f32_16x16x32_bf16 v[186:189], v[102:105], v[202:205], v[186:189]
	v_mfma_f32_16x16x32_bf16 v[34:37], v[134:137], v[202:205], v[34:37]
	v_mfma_f32_16x16x32_bf16 v[182:185], v[166:169], v[202:205], v[182:185]
	ds_read2_b64 v[234:237], v207 offset1:4
	ds_read2_b64 v[202:205], v207 offset0:8 offset1:12
	s_waitcnt lgkmcnt(2)
	v_mfma_f32_16x16x32_bf16 v[226:229], v[74:77], v[230:233], v[226:229]
	v_mfma_f32_16x16x32_bf16 v[186:189], v[106:109], v[230:233], v[186:189]
	v_mfma_f32_16x16x32_bf16 v[34:37], v[138:141], v[230:233], v[34:37]
	v_mfma_f32_16x16x32_bf16 v[182:185], v[170:173], v[230:233], v[182:185]
	v_mfma_f32_16x16x32_bf16 v[226:229], v[78:81], v[238:241], v[226:229]
	v_mfma_f32_16x16x32_bf16 v[186:189], v[110:113], v[238:241], v[186:189]
	v_mfma_f32_16x16x32_bf16 v[34:37], v[142:145], v[238:241], v[34:37]
	v_mfma_f32_16x16x32_bf16 v[182:185], v[174:177], v[238:241], v[182:185]
	ds_read_b128 v[230:233], v225 offset:2560
	ds_read_b128 v[238:241], v208 offset:47232
	s_nop 5
	v_mul_f32_e32 v206, v227, v227
	v_mul_f32_e32 v209, v187, v187
	v_fmac_f32_e32 v206, v226, v226
	v_fmac_f32_e32 v209, v186, v186
	v_fmac_f32_e32 v206, v228, v228
	v_fmac_f32_e32 v209, v188, v188
	v_fmac_f32_e32 v206, v229, v229
	v_fmac_f32_e32 v209, v189, v189
	v_add_f32_e32 v206, v206, v209
	v_mul_f32_e32 v209, v35, v35
	v_fmac_f32_e32 v209, v34, v34
	v_fmac_f32_e32 v209, v36, v36
	v_fmac_f32_e32 v209, v37, v37
	v_add_f32_e32 v206, v206, v209
	v_mul_f32_e32 v209, v183, v183
	v_fmac_f32_e32 v209, v182, v182
	v_fmac_f32_e32 v209, v184, v184
	v_fmac_f32_e32 v209, v185, v185
	v_add_f32_e32 v206, v206, v209
	v_mov_b32_e32 v209, v206
	s_nop 1
	v_permlane16_swap_b32_e32 v206, v209
	v_add_f32_e32 v206, v206, v209
	v_mov_b32_e32 v209, v206
	s_nop 1
	v_permlane32_swap_b32_e32 v206, v209
	v_add_f32_e32 v206, v206, v209
	v_mov_b32_e32 v209, 0x358637bd
	v_fmamk_f32 v206, v206, 0x3c800000, v209
	v_rsq_f32_e32 v206, v206
	s_nop 0
	v_mul_f32_e32 v226, v226, v206
	v_mul_f32_e32 v227, v227, v206
	v_mul_f32_e32 v228, v228, v206
	v_mul_f32_e32 v229, v229, v206
	v_mul_f32_e32 v186, v186, v206
	v_mul_f32_e32 v187, v187, v206
	v_mul_f32_e32 v188, v188, v206
	v_mul_f32_e32 v189, v189, v206
	v_mul_f32_e32 v34, v34, v206
	v_mul_f32_e32 v35, v35, v206
	v_mul_f32_e32 v36, v36, v206
	v_mul_f32_e32 v37, v37, v206
	v_mul_f32_e32 v182, v182, v206
	v_mul_f32_e32 v183, v183, v206
	v_mul_f32_e32 v184, v184, v206
	v_mul_f32_e32 v185, v185, v206
	v_cvt_pk_bf16_f32 v226, v226, v227
	v_cvt_pk_bf16_f32 v227, v228, v229
	v_cvt_pk_bf16_f32 v228, v186, v187
	v_cvt_pk_bf16_f32 v229, v188, v189
	v_cvt_pk_bf16_f32 v34, v34, v35
	v_cvt_pk_bf16_f32 v35, v36, v37
	v_cvt_pk_bf16_f32 v36, v182, v183
	v_cvt_pk_bf16_f32 v37, v184, v185
	ds_read_b128 v[186:189], v49 offset:12288
	ds_read_b128 v[182:185], v48 offset:12288
	s_waitcnt lgkmcnt(2)
	v_mfma_f32_16x16x32_bf16 v[242:245], v[226:229], v[234:237], 0
	v_mfma_f32_16x16x32_bf16 v[242:245], v[34:37], v[202:205], v[242:245]
	v_mfma_f32_16x16x32_bf16 v[242:245], v[230:233], v[238:241], v[242:245]
	ds_read_b128 v[234:237], v47 offset:12288
	ds_read_b128 v[202:205], v46 offset:12288
	s_waitcnt lgkmcnt(2)
	v_mfma_f32_16x16x32_bf16 v[226:229], v[50:53], v[186:189], 0
	v_mfma_f32_16x16x32_bf16 v[34:37], v[82:85], v[186:189], 0
	v_mfma_f32_16x16x32_bf16 v[230:233], v[114:117], v[186:189], 0
	v_mfma_f32_16x16x32_bf16 v[238:241], v[146:149], v[186:189], 0
	v_mfma_f32_16x16x32_bf16 v[226:229], v[54:57], v[182:185], v[226:229]
	v_mfma_f32_16x16x32_bf16 v[34:37], v[86:89], v[182:185], v[34:37]
	v_mfma_f32_16x16x32_bf16 v[230:233], v[118:121], v[182:185], v[230:233]
	v_mfma_f32_16x16x32_bf16 v[238:241], v[150:153], v[182:185], v[238:241]
	ds_read_b128 v[186:189], v49 offset:28672
	ds_read_b128 v[182:185], v48 offset:28672
	s_waitcnt lgkmcnt(2)
	v_mfma_f32_16x16x32_bf16 v[226:229], v[58:61], v[234:237], v[226:229]
	v_mfma_f32_16x16x32_bf16 v[34:37], v[90:93], v[234:237], v[34:37]
	v_mfma_f32_16x16x32_bf16 v[230:233], v[122:125], v[234:237], v[230:233]
	v_mfma_f32_16x16x32_bf16 v[238:241], v[154:157], v[234:237], v[238:241]
	v_mfma_f32_16x16x32_bf16 v[226:229], v[62:65], v[202:205], v[226:229]
	v_mfma_f32_16x16x32_bf16 v[34:37], v[94:97], v[202:205], v[34:37]
	v_mfma_f32_16x16x32_bf16 v[230:233], v[126:129], v[202:205], v[230:233]
	v_mfma_f32_16x16x32_bf16 v[238:241], v[158:161], v[202:205], v[238:241]
	ds_read_b128 v[234:237], v47 offset:28672
	ds_read_b128 v[202:205], v46 offset:28672
	s_waitcnt lgkmcnt(2)
	v_mfma_f32_16x16x32_bf16 v[226:229], v[66:69], v[186:189], v[226:229]
	v_mfma_f32_16x16x32_bf16 v[34:37], v[98:101], v[186:189], v[34:37]
	v_mfma_f32_16x16x32_bf16 v[230:233], v[130:133], v[186:189], v[230:233]
	v_mfma_f32_16x16x32_bf16 v[238:241], v[162:165], v[186:189], v[238:241]
	v_mfma_f32_16x16x32_bf16 v[226:229], v[70:73], v[182:185], v[226:229]
	v_mfma_f32_16x16x32_bf16 v[34:37], v[102:105], v[182:185], v[34:37]
	v_mfma_f32_16x16x32_bf16 v[230:233], v[134:137], v[182:185], v[230:233]
	v_mfma_f32_16x16x32_bf16 v[238:241], v[166:169], v[182:185], v[238:241]
	ds_read2_b64 v[186:189], v207 offset1:4
	ds_read2_b64 v[182:185], v207 offset0:8 offset1:12
	s_waitcnt lgkmcnt(2)
	v_mfma_f32_16x16x32_bf16 v[226:229], v[74:77], v[234:237], v[226:229]
	v_mfma_f32_16x16x32_bf16 v[34:37], v[106:109], v[234:237], v[34:37]
	v_mfma_f32_16x16x32_bf16 v[230:233], v[138:141], v[234:237], v[230:233]
	v_mfma_f32_16x16x32_bf16 v[238:241], v[170:173], v[234:237], v[238:241]
	v_mfma_f32_16x16x32_bf16 v[226:229], v[78:81], v[202:205], v[226:229]
	v_mfma_f32_16x16x32_bf16 v[34:37], v[110:113], v[202:205], v[34:37]
	v_mfma_f32_16x16x32_bf16 v[230:233], v[142:145], v[202:205], v[230:233]
	v_mfma_f32_16x16x32_bf16 v[238:241], v[174:177], v[202:205], v[238:241]
	ds_read_b128 v[234:237], v225 offset:3840
	ds_read_b128 v[202:205], v208 offset:47232
	s_nop 5
	v_mul_f32_e32 v206, v227, v227
	v_mul_f32_e32 v209, v35, v35
	v_fmac_f32_e32 v206, v226, v226
	v_fmac_f32_e32 v209, v34, v34
	v_fmac_f32_e32 v206, v228, v228
	v_fmac_f32_e32 v209, v36, v36
	v_fmac_f32_e32 v206, v229, v229
	v_fmac_f32_e32 v209, v37, v37
	v_add_f32_e32 v206, v206, v209
	v_mul_f32_e32 v209, v231, v231
	v_fmac_f32_e32 v209, v230, v230
	v_fmac_f32_e32 v209, v232, v232
	v_fmac_f32_e32 v209, v233, v233
	v_add_f32_e32 v206, v206, v209
	v_mul_f32_e32 v209, v239, v239
	v_fmac_f32_e32 v209, v238, v238
	v_fmac_f32_e32 v209, v240, v240
	v_fmac_f32_e32 v209, v241, v241
	v_add_f32_e32 v206, v206, v209
	v_mov_b32_e32 v209, v206
	s_nop 1
	v_permlane16_swap_b32_e32 v206, v209
	v_add_f32_e32 v206, v206, v209
	v_mov_b32_e32 v209, v206
	s_nop 1
	v_permlane32_swap_b32_e32 v206, v209
	v_add_f32_e32 v206, v206, v209
	v_mov_b32_e32 v209, 0x358637bd
	v_fmamk_f32 v206, v206, 0x3c800000, v209
	v_rsq_f32_e32 v206, v206
	s_nop 0
	v_mul_f32_e32 v226, v226, v206
	v_mul_f32_e32 v227, v227, v206
	v_mul_f32_e32 v228, v228, v206
	v_mul_f32_e32 v229, v229, v206
	v_mul_f32_e32 v34, v34, v206
	v_mul_f32_e32 v35, v35, v206
	v_mul_f32_e32 v36, v36, v206
	v_mul_f32_e32 v37, v37, v206
	v_mul_f32_e32 v230, v230, v206
	v_mul_f32_e32 v231, v231, v206
	v_mul_f32_e32 v232, v232, v206
	v_mul_f32_e32 v233, v233, v206
	v_mul_f32_e32 v238, v238, v206
	v_mul_f32_e32 v239, v239, v206
	v_mul_f32_e32 v240, v240, v206
	v_mul_f32_e32 v241, v241, v206
	v_cvt_pk_bf16_f32 v226, v226, v227
	v_cvt_pk_bf16_f32 v227, v228, v229
	v_cvt_pk_bf16_f32 v228, v34, v35
	v_cvt_pk_bf16_f32 v229, v36, v37
	v_cvt_pk_bf16_f32 v230, v230, v231
	v_cvt_pk_bf16_f32 v231, v232, v233
	v_cvt_pk_bf16_f32 v232, v238, v239
	v_cvt_pk_bf16_f32 v233, v240, v241
	s_waitcnt lgkmcnt(0)
	v_mfma_f32_16x16x32_bf16 v[246:249], v[226:229], v[186:189], 0
	v_mfma_f32_16x16x32_bf16 v[246:249], v[230:233], v[182:185], v[246:249]
	v_mfma_f32_16x16x32_bf16 v[246:249], v[234:237], v[202:205], v[246:249]
	s_nop 7
	s_and_b64 vcc, exec, s[22:23]
	s_cbranch_vccz .Lsa_nomask
	v_cmp_le_u32_e32 vcc, v218, v220
	s_nop 1
	v_cndmask_b32_e32 v38, v211, v38, vcc
	v_add_u32_e32 v206, 1, v218
	v_cmp_le_u32_e32 vcc, v206, v220
	s_nop 1
	v_cndmask_b32_e32 v39, v211, v39, vcc
	v_add_u32_e32 v206, 2, v218
	v_cmp_le_u32_e32 vcc, v206, v220
	s_nop 1
	v_cndmask_b32_e32 v40, v211, v40, vcc
	v_add_u32_e32 v206, 3, v218
	v_cmp_le_u32_e32 vcc, v206, v220
	s_nop 1
	v_cndmask_b32_e32 v41, v211, v41, vcc
	v_mov_b32_e32 v178, v211
	v_mov_b32_e32 v179, v211
	v_mov_b32_e32 v180, v211
	v_mov_b32_e32 v181, v211
	v_mov_b32_e32 v242, v211
	v_mov_b32_e32 v243, v211
	v_mov_b32_e32 v244, v211
	v_mov_b32_e32 v245, v211
	v_mov_b32_e32 v246, v211
	v_mov_b32_e32 v247, v211
	v_mov_b32_e32 v248, v211
	v_mov_b32_e32 v249, v211

.Lsa_pdone:
	s_or_b64 exec, exec, s[24:25]
	v_lshrrev_b32_e32 v34, 3, v43
	v_and_b32_e32 v38, 12, v43
	v_and_or_b32 v34, v34, 2, s40
	v_bfe_u32 v35, v43, 1, 1
	v_and_or_b32 v39, v45, 2, v38
	v_or_b32_e32 v36, v34, v35
	v_lshlrev_b32_e32 v37, 8, v44
	v_bitop3_b32 v34, v34, v39, v35 bitop3:0x36
	v_lshlrev_b32_e32 v35, 3, v43
	v_and_b32_e32 v37, 0xfffffb00, v37
	v_and_b32_e32 v35, 8, v35
	v_lshl_add_u32 v34, v34, 4, s39
	v_add3_u32 v34, v34, v37, v35
	v_or_b32_e32 v37, 4, v44
	v_lshlrev_b32_e32 v39, 8, v37
	v_bfe_u32 v37, v37, 2, 2
	v_bitop3_b32 v36, v37, v36, v38 bitop3:0x36
	v_lshl_add_u32 v36, v36, 4, s39
	v_add3_u32 v35, v36, v39, v35
	v_add_u32_e32 v36, 0x2000, v34
	v_add_u32_e32 v37, 0x2000, v35
	v_add_u32_e32 v40, 0xec00, v221
	s_waitcnt lgkmcnt(0)
	s_barrier
	ds_read2_b32 v[44:45], v40 offset0:52 offset1:84
	ds_read_b64_tr_b16 v[226:227], v34
	ds_read_b64_tr_b16 v[228:229], v35
	ds_read_b64_tr_b16 v[186:187], v34 offset:4096
	ds_read_b64_tr_b16 v[188:189], v35 offset:4096
	ds_read_b64_tr_b16 v[182:183], v36
	ds_read_b64_tr_b16 v[184:185], v37
	ds_read_b64_tr_b16 v[178:179], v36 offset:4096
	ds_read_b64_tr_b16 v[180:181], v37 offset:4096
	s_waitcnt lgkmcnt(8)
	v_mul_f32_e32 v2, v44, v2
	v_mul_f32_e32 v3, v44, v3
	v_mul_f32_e32 v4, v44, v4
	v_mul_f32_e32 v5, v44, v5
	v_mul_f32_e32 v6, v44, v6
	v_mul_f32_e32 v7, v44, v7
	v_mul_f32_e32 v8, v44, v8
	v_mul_f32_e32 v9, v44, v9
	v_mul_f32_e32 v10, v44, v10
	v_mul_f32_e32 v11, v44, v11
	v_mul_f32_e32 v12, v44, v12
	v_mul_f32_e32 v13, v44, v13
	v_mul_f32_e32 v14, v44, v14
	v_mul_f32_e32 v15, v44, v15
	v_mul_f32_e32 v16, v44, v16
	v_mul_f32_e32 v17, v44, v17
	v_mul_f32_e32 v18, v45, v18
	v_mul_f32_e32 v19, v45, v19
	v_mul_f32_e32 v20, v45, v20
	v_mul_f32_e32 v21, v45, v21
	v_mul_f32_e32 v22, v45, v22
	v_mul_f32_e32 v23, v45, v23
	v_mul_f32_e32 v24, v45, v24
	v_mul_f32_e32 v25, v45, v25
	v_mul_f32_e32 v26, v45, v26
	v_mul_f32_e32 v27, v45, v27
	v_mul_f32_e32 v28, v45, v28
	v_mul_f32_e32 v29, v45, v29
	v_mul_f32_e32 v30, v45, v30
	v_mul_f32_e32 v31, v45, v31
	v_mul_f32_e32 v32, v45, v32
	v_mul_f32_e32 v33, v45, v33
	s_waitcnt lgkmcnt(4)
	ds_read_b128 v[230:233], v222 offset:37888
	ds_read_b128 v[234:237], v222 offset:42496
	ds_read_b128 v[238:241], v222 offset:37920
	ds_read_b128 v[242:245], v222 offset:42528
	ds_read_b128 v[246:249], v222 offset:37952
	ds_read_b128 v[206:209], v222 offset:42560
	ds_read_b128 v[46:49], v222 offset:37984
	ds_read_b128 v[38:41], v222 offset:42592
	s_waitcnt lgkmcnt(6)
	v_mfma_f32_32x32x16_bf16 v[2:17], v[226:229], v[230:233], v[2:17]
	v_mfma_f32_32x32x16_bf16 v[18:33], v[226:229], v[234:237], v[18:33]
	s_waitcnt lgkmcnt(4)
	v_mfma_f32_32x32x16_bf16 v[2:17], v[186:189], v[238:241], v[2:17]
	v_mfma_f32_32x32x16_bf16 v[18:33], v[186:189], v[242:245], v[18:33]
	s_waitcnt lgkmcnt(2)
	v_mfma_f32_32x32x16_bf16 v[2:17], v[182:185], v[246:249], v[2:17]
	v_mfma_f32_32x32x16_bf16 v[18:33], v[182:185], v[206:209], v[18:33]
	s_waitcnt lgkmcnt(0)
	v_mfma_f32_32x32x16_bf16 v[2:17], v[178:181], v[46:49], v[2:17]
	v_mfma_f32_32x32x16_bf16 v[18:33], v[178:181], v[38:41], v[18:33]
	s_cmp_lt_u32 s41, s37
	s_cbranch_scc0 .LBB0_828
	s_mov_b64 s[10:11], -1
	s_and_b64 vcc, exec, s[18:19]
	s_cbranch_vccz .LBB0_825
	s_waitcnt lgkmcnt(0)
	s_barrier
	s_and_saveexec_b64 s[18:19], s[12:13]
	s_cbranch_execz .LBB0_824
	s_mov_b64 s[20:21], 0
	v_mov_b32_e32 v40, v250
	s_branch .LBB0_818
